# stick-breaking tile loop: K and V^T tiles loaded global->LDS directly (LDS-DMA, swizzle on the source offsets) instead of through VGPRs and ds_write_b128
# baseline (speedup 1.0000x reference)
.LBB0_247:
	s_and_b32 s27, s15, 0xff
	s_ashr_i32 s42, s15, 12
	v_mov_b32_e32 v38, v208
	s_ashr_i32 s43, s42, 31
	v_and_b32_e32 v78, 31, v38
	s_lshl_b32 s8, s27, 5
	s_lshl_b64 s[0:1], s[42:43], 13
	v_or_b32_e32 v79, s8, v78
	v_or_b32_e32 v146, s0, v79
	v_mov_b32_e32 v147, s1
	s_lshr_b32 s1, s15, 1
	v_lshlrev_b64 v[2:3], 12, v[146:147]
	s_and_b32 s9, s1, 0x780
	v_bfe_u32 v68, v38, 5, 1
	v_lshl_add_u64 v[2:3], s[4:5], 0, v[2:3]
	s_lshl_b32 s40, s9, 1
	s_mov_b32 s41, s85
	v_lshl_add_u64 v[2:3], v[2:3], 0, s[40:41]
	v_lshlrev_b32_e32 v0, 4, v68
	v_lshl_add_u64 v[2:3], v[2:3], 0, v[0:1]
	global_load_dwordx4 v[82:85], v[2:3], off
	global_load_dwordx4 v[86:89], v[2:3], off offset:32
	global_load_dwordx4 v[90:93], v[2:3], off offset:64
	global_load_dwordx4 v[94:97], v[2:3], off offset:96
	global_load_dwordx4 v[98:101], v[2:3], off offset:128
	global_load_dwordx4 v[102:105], v[2:3], off offset:160
	global_load_dwordx4 v[106:109], v[2:3], off offset:192
	global_load_dwordx4 v[110:113], v[2:3], off offset:224
	s_lshl_b32 s10, s42, 7
	v_bfe_u32 v69, v38, 4, 2
	s_ashr_i32 s11, s10, 31
	v_lshrrev_b32_e32 v3, 1, v38
	v_or_b32_e32 v2, s0, v69
	s_lshl_b64 s[0:1], s[10:11], 11
	v_and_b32_e32 v37, 4, v3
	v_mov_b32_e32 v3, v147
	v_readlane_b32 s10, v252, 51
	v_lshlrev_b64 v[2:3], 12, v[2:3]
	v_readlane_b32 s11, v252, 52
	v_lshlrev_b32_e32 v0, 1, v38
	v_lshlrev_b32_e32 v71, 4, v38
	v_lshl_add_u64 v[2:3], s[10:11], 0, v[2:3]
	v_and_b32_e32 v36, 8, v0
	v_lshl_add_u64 v[2:3], v[2:3], 0, s[40:41]
	v_and_b32_e32 v0, 0xf0, v71
	s_lshl_b32 s84, s27, 17
	v_lshl_add_u64 v[150:151], v[2:3], 0, v[0:1]
	v_lshl_add_u64 v[30:31], v[150:151], 0, s[84:85]
	v_add_co_u32_e32 v6, vcc, s81, v30
	v_bfe_u32 v70, v38, 2, 4
	s_nop 0
	v_addc_co_u32_e32 v7, vcc, 0, v31, vcc
	v_add_co_u32_e32 v10, vcc, s82, v30
	v_and_b32_e32 v34, 19, v38
	s_nop 0
	v_addc_co_u32_e32 v11, vcc, 0, v31, vcc
	v_add_co_u32_e32 v14, vcc, s76, v30
	v_or_b32_e32 v48, s0, v70
	s_nop 0
	v_addc_co_u32_e32 v15, vcc, 0, v31, vcc
	v_add_co_u32_e32 v18, vcc, s70, v30
	v_mov_b32_e32 v35, s1
	s_nop 0
	v_addc_co_u32_e32 v19, vcc, 0, v31, vcc
	v_add_co_u32_e32 v22, vcc, s80, v30
	v_or3_b32 v76, v37, v34, v36
	s_nop 0
	v_addc_co_u32_e32 v23, vcc, 0, v31, vcc
	v_add_co_u32_e32 v26, vcc, s71, v30
	v_or_b32_e32 v34, s9, v48
	s_nop 0
	v_addc_co_u32_e32 v27, vcc, 0, v31, vcc
	v_readlane_b32 s0, v252, 53
	v_xor_b32_e32 v0, v69, v38
	v_or_b32_e32 v212, s9, v70
	v_lshlrev_b64 v[34:35], 7, v[34:35]
	v_lshlrev_b32_e32 v212, 6, v212
	s_nop 0
	v_sub_co_u32_e32 v34, vcc, v34, v212
	s_nop 1
	v_subbrev_co_u32_e32 v35, vcc, 0, v35, vcc
	v_readlane_b32 s1, v252, 54
	v_lshlrev_b32_e32 v77, 4, v0
	v_and_b32_e32 v0, 48, v71
	v_lshl_add_u64 v[34:35], s[0:1], 0, v[34:35]
	s_lshl_b32 s6, s15, 6
	v_lshl_add_u64 v[152:153], v[34:35], 0, v[0:1]
	s_waitcnt vmcnt(7)
	s_waitcnt vmcnt(6)
	s_waitcnt vmcnt(5)
	s_waitcnt vmcnt(4)
	s_waitcnt vmcnt(3)
	s_waitcnt vmcnt(2)
	s_waitcnt vmcnt(1)
	s_waitcnt vmcnt(0)
	global_load_dwordx4 v[2:5], v[30:31], off
	s_nop 0
	global_load_dwordx4 v[6:9], v[6:7], off
	s_nop 0
	global_load_dwordx4 v[10:13], v[10:11], off
	s_nop 0
	global_load_dwordx4 v[14:17], v[14:15], off
	s_nop 0
	global_load_dwordx4 v[18:21], v[18:19], off
	s_nop 0
	global_load_dwordx4 v[22:25], v[22:23], off
	v_add_co_u32_e32 v30, vcc, s83, v30
	global_load_dwordx4 v[26:29], v[26:27], off
	s_nop 0
	v_addc_co_u32_e32 v31, vcc, 0, v31, vcc
	global_load_dwordx4 v[30:33], v[30:31], off
	s_and_b32 s84, s84, 0x1fc0000
	v_lshl_add_u64 v[34:35], v[152:153], 0, s[84:85]
	s_and_b32 s84, s6, 64
	s_lshl_b32 s84, s84, 11
	v_lshl_add_u64 v[52:53], v[34:35], 0, s[84:85]
	v_add_co_u32_e32 v48, vcc, s77, v52
	v_or_b32_e32 v40, 4, v69
	s_nop 0
	v_addc_co_u32_e32 v49, vcc, 0, v53, vcc
	v_bitop3_b32 v41, v69, v38, 4 bitop3:0x36
	v_or_b32_e32 v42, 8, v69
	v_bitop3_b32 v43, v69, v38, 8 bitop3:0x36
	v_or_b32_e32 v44, 12, v69
	v_bitop3_b32 v45, v69, v38, 12 bitop3:0x36
	v_or_b32_e32 v46, 20, v69
	v_bitop3_b32 v47, v69, v38, 20 bitop3:0x36
	v_add_co_u32_e32 v56, vcc, s77, v52
	v_lshl_add_u32 v80, v40, 8, s33
	v_lshlrev_b32_e32 v81, 4, v41
	v_lshl_add_u32 v114, v42, 8, s33
	v_lshlrev_b32_e32 v115, 4, v43
	v_lshl_add_u32 v116, v44, 8, s33
	v_lshlrev_b32_e32 v117, 4, v45
	v_lshl_add_u32 v118, v46, 8, s33
	v_lshlrev_b32_e32 v119, 4, v47
	v_addc_co_u32_e32 v57, vcc, 0, v53, vcc
	global_load_dwordx4 v[34:37], v[52:53], off
	global_load_dwordx4 v[40:43], v[52:53], off offset:1024
	global_load_dwordx4 v[44:47], v[52:53], off offset:2048
	s_nop 0
	global_load_dwordx4 v[48:51], v[52:53], off offset:3072
	v_add_co_u32_e32 v64, vcc, s77, v52
	v_lshl_add_u32 v75, v69, 8, s33
	s_nop 0
	v_addc_co_u32_e32 v65, vcc, 0, v53, vcc
	global_load_dwordx4 v[52:55], v[56:57], off
	s_nop 0
	global_load_dwordx4 v[56:59], v[56:57], off offset:1024
	s_nop 0
	global_load_dwordx4 v[60:63], v[64:65], off offset:2048
	s_nop 0
	global_load_dwordx4 v[64:67], v[64:65], off offset:3072
	v_and_b32_e32 v0, 0xf0, v77
	v_and_b32_e32 v77, 0xf0, v81
	v_and_b32_e32 v81, 0xf0, v115
	v_and_b32_e32 v115, 0xf0, v117
	v_and_b32_e32 v117, 0xf0, v119
	v_add_u32_e32 v0, v75, v0
	v_add_u32_e32 v149, v80, v77
	v_add_u32_e32 v174, v114, v81
	v_add_u32_e32 v175, v116, v115
	v_add_u32_e32 v176, v118, v117
	v_bitop3_b32 v121, v76, v68, 15 bitop3:0x6c
	v_lshlrev_b32_e32 v120, 8, v76
	v_or_b32_e32 v72, 2, v68
	v_bitop3_b32 v72, v76, v72, 15 bitop3:0x6c
	v_or_b32_e32 v73, 4, v68
	v_bitop3_b32 v73, v76, v73, 15 bitop3:0x6c
	v_or_b32_e32 v74, 6, v68
	v_lshlrev_b32_e32 v148, 3, v68
	v_and_b32_e32 v39, 63, v38
	v_cmp_lt_u32_e64 s[68:69], v148, v78
	s_waitcnt vmcnt(15)
	ds_write_b128 v0, v[2:5]
	s_waitcnt vmcnt(14)
	ds_write_b128 v149, v[6:9]
	s_waitcnt vmcnt(13)
	ds_write_b128 v174, v[10:13]
	s_waitcnt vmcnt(12)
	ds_write_b128 v175, v[14:17]
	s_waitcnt vmcnt(11)
	ds_write_b128 v0, v[18:21] offset:4096
	s_waitcnt vmcnt(10)
	ds_write_b128 v176, v[22:25]
	v_bitop3_b32 v3, v69, v38, 24 bitop3:0x36
	v_or_b32_e32 v2, 24, v69
	v_lshlrev_b32_e32 v3, 4, v3
	v_lshl_add_u32 v2, v2, 8, s33
	v_and_b32_e32 v3, 0xf0, v3
	v_add_u32_e32 v177, v2, v3
	v_bitop3_b32 v3, v69, v38, 28 bitop3:0x36
	v_or_b32_e32 v2, 28, v69
	v_lshlrev_b32_e32 v3, 4, v3
	v_lshl_add_u32 v2, v2, 8, s33
	v_and_b32_e32 v3, 0xf0, v3
	v_add_u32_e32 v178, v2, v3
	v_lshl_add_u32 v2, v121, 4, s33
	s_waitcnt vmcnt(9)
	ds_write_b128 v177, v[26:29]
	s_waitcnt vmcnt(8)
	ds_write_b128 v178, v[30:33]
	v_add_u32_e32 v179, v2, v120
	ds_read_b128 v[2:5], v179
	v_or_b32_e32 v6, 8, v68
	v_bitop3_b32 v27, v76, v6, 15 bitop3:0x6c
	v_or_b32_e32 v6, 10, v68
	v_bitop3_b32 v28, v76, v6, 15 bitop3:0x6c
	v_lshl_add_u32 v6, v72, 4, s33
	v_add_u32_e32 v180, v6, v120
	ds_read_b128 v[18:21], v180
	s_waitcnt lgkmcnt(1)
	v_mfma_f32_32x32x16_bf16 v[2:17], v[2:5], v[82:85], 0
	v_or_b32_e32 v22, 12, v68
	v_bitop3_b32 v29, v76, v22, 15 bitop3:0x6c
	v_or_b32_e32 v22, 14, v68
	v_bitop3_b32 v30, v76, v22, 15 bitop3:0x6c
	v_lshl_add_u32 v22, v73, 4, s33
	v_add_u32_e32 v181, v22, v120
	ds_read_b128 v[22:25], v181
	s_waitcnt lgkmcnt(1)
	v_mfma_f32_32x32x16_bf16 v[2:17], v[18:21], v[86:89], v[2:17]
	v_bitop3_b32 v26, v76, v74, 15 bitop3:0x6c
	v_lshrrev_b32_e32 v18, 2, v38
	v_bitop3_b32 v33, v68, v18, 3 bitop3:0x78
	v_lshl_add_u32 v18, v26, 4, s33
	v_add_u32_e32 v182, v18, v120
	ds_read_b128 v[18:21], v182
	v_bfe_u32 v32, v38, 2, 2
	s_waitcnt lgkmcnt(1)
	v_mfma_f32_32x32x16_bf16 v[2:17], v[22:25], v[90:93], v[2:17]
	v_lshl_add_u32 v22, v70, 6, s33
	v_bitop3_b32 v23, v71, 48, v38 bitop3:0x48
	v_add_u32_e32 v183, v22, v23
	v_lshl_add_u32 v22, v27, 4, s33
	v_add_u32_e32 v184, v22, v120
	ds_read_b128 v[22:25], v184
	s_waitcnt vmcnt(7)
	ds_write_b128 v183, v[34:37] offset:8192
	s_waitcnt vmcnt(6)
	ds_write_b128 v183, v[40:43] offset:9216
	s_waitcnt vmcnt(5)
	ds_write_b128 v183, v[44:47] offset:10240
	s_waitcnt vmcnt(4)
	ds_write_b128 v183, v[48:51] offset:11264
	s_waitcnt lgkmcnt(5)
	v_mfma_f32_32x32x16_bf16 v[2:17], v[18:21], v[94:97], v[2:17]
	v_lshl_add_u32 v18, v28, 4, s33
	v_add_u32_e32 v185, v18, v120
	ds_read_b128 v[18:21], v185
	s_waitcnt vmcnt(3)
	ds_write_b128 v183, v[52:55] offset:12288
	s_waitcnt vmcnt(2)
	ds_write_b128 v183, v[56:59] offset:13312
	s_waitcnt vmcnt(1)
	ds_write_b128 v183, v[60:63] offset:14336
	s_waitcnt vmcnt(0)
	ds_write_b128 v183, v[64:67] offset:15360
	v_or_b32_e32 v38, s8, v148
	v_lshlrev_b32_e32 v31, 6, v78
	v_bitop3_b32 v26, v68, v32, 2 bitop3:0x36
	s_waitcnt lgkmcnt(9)
	v_mfma_f32_32x32x16_bf16 v[2:17], v[22:25], v[98:101], v[2:17]
	v_lshl_add_u32 v22, v29, 4, s33
	v_add_u32_e32 v186, v22, v120
	ds_read_b128 v[22:25], v186
	s_waitcnt lgkmcnt(5)
	v_mfma_f32_32x32x16_bf16 v[2:17], v[18:21], v[102:105], v[2:17]
	v_lshl_add_u32 v18, v30, 4, s33
	v_add_u32_e32 v187, v18, v120
	ds_read_b128 v[40:43], v187
	v_lshl_or_b32 v18, v33, 4, v31
	v_add_u32_e32 v188, s33, v18
	v_lshl_or_b32 v18, v26, 4, v31
	v_add_u32_e32 v189, s33, v18
	s_waitcnt lgkmcnt(1)
	v_mfma_f32_32x32x16_bf16 v[2:17], v[22:25], v[106:109], v[2:17]
	ds_read_b128 v[34:37], v188 offset:8192
	ds_read_b128 v[18:21], v188 offset:10240
	ds_read_b128 v[30:33], v189 offset:8192
	ds_read_b128 v[22:25], v189 offset:10240
	ds_read_b128 v[26:29], v188 offset:12288
	ds_read_b128 v[70:73], v188 offset:14336
	ds_read_b128 v[74:77], v189 offset:12288
	ds_read_b128 v[66:69], v189 offset:14336
	s_waitcnt lgkmcnt(8)
	v_mfma_f32_32x32x16_bf16 v[2:17], v[40:43], v[110:113], v[2:17]
	v_or_b32_e32 v41, 22, v38
	v_cmp_lt_u32_e32 vcc, v41, v79
	v_or_b32_e32 v41, 21, v38
	v_cmp_lt_u32_e64 s[0:1], v41, v79
	v_or_b32_e32 v41, 20, v38
	v_cmp_lt_u32_e64 s[42:43], v41, v79
	v_or_b32_e32 v41, 19, v38
	v_cmp_lt_u32_e64 s[44:45], v41, v79
	v_or_b32_e32 v41, 18, v38
	v_cmp_lt_u32_e64 s[46:47], v41, v79
	v_or_b32_e32 v41, 17, v38
	v_cmp_lt_u32_e64 s[50:51], v41, v79
	v_or_b32_e32 v41, 16, v38
	v_cmp_lt_u32_e64 s[52:53], v41, v79
	v_or_b32_e32 v41, 7, v38
	v_cmp_lt_u32_e64 s[54:55], v41, v79
	v_or_b32_e32 v41, 6, v38
	v_cmp_lt_u32_e64 s[56:57], v41, v79
	v_or_b32_e32 v41, 5, v38
	v_or_b32_e32 v40, 23, v38
	v_cmp_lt_u32_e64 s[58:59], v41, v79
	v_or_b32_e32 v41, 4, v38
	v_cmp_lt_u32_e64 s[60:61], v41, v79
	v_or_b32_e32 v41, 3, v38
	v_cndmask_b32_e64 v42, v211, v2, s[68:69]
	v_cmp_lt_u32_e64 s[68:69], v40, v79
	v_cmp_lt_u32_e64 s[62:63], v41, v79
	v_or_b32_e32 v41, 2, v38
	s_or_b64 vcc, s[68:69], vcc
	v_cmp_lt_u32_e64 s[64:65], v41, v79
	v_cndmask_b32_e32 v41, v211, v16, vcc
	s_or_b64 vcc, vcc, s[0:1]
	v_or_b32_e32 v38, 1, v38
	v_cndmask_b32_e32 v15, v211, v15, vcc
	s_or_b64 vcc, vcc, s[42:43]
	v_cmp_lt_u32_e64 s[66:67], v38, v79
	v_cndmask_b32_e32 v38, v211, v14, vcc
	s_or_b64 vcc, vcc, s[44:45]
	v_cndmask_b32_e32 v16, v211, v13, vcc
	s_or_b64 vcc, vcc, s[46:47]
	v_cndmask_b32_e32 v14, v211, v12, vcc
	s_or_b64 vcc, vcc, s[50:51]
	v_cndmask_b32_e32 v12, v211, v11, vcc
	s_or_b64 vcc, vcc, s[52:53]
	v_cndmask_b32_e32 v2, v211, v10, vcc
	s_or_b64 vcc, vcc, s[54:55]
	v_cndmask_b32_e32 v9, v211, v9, vcc
	s_or_b64 vcc, vcc, s[56:57]
	v_cndmask_b32_e32 v8, v211, v8, vcc
	s_or_b64 vcc, vcc, s[58:59]
	v_cndmask_b32_e32 v10, v211, v7, vcc
	s_or_b64 vcc, vcc, s[60:61]
	v_cndmask_b32_e32 v6, v211, v6, vcc
	s_or_b64 vcc, vcc, s[62:63]
	v_cndmask_b32_e32 v44, v211, v5, vcc
	v_mul_f32_e64 v5, |v42|, s79
	v_exp_f32_e32 v5, v5
	s_or_b64 vcc, vcc, s[64:65]
	v_cndmask_b32_e32 v4, v211, v4, vcc
	s_or_b64 vcc, vcc, s[66:67]
	v_cndmask_b32_e32 v46, v211, v3, vcc
	v_max_f32_e32 v3, v42, v42
	v_max_f32_e32 v48, 0, v3
	v_add_f32_e32 v3, 1.0, v5
	v_mul_f32_e64 v5, |v46|, s79
	v_exp_f32_e32 v5, v5
	v_log_f32_e32 v50, v3
	v_max_f32_e32 v3, v46, v46
	v_max_f32_e32 v49, 0, v3
	v_add_f32_e32 v3, 1.0, v5
	v_mul_f32_e64 v5, |v4|, s79
	v_exp_f32_e32 v5, v5
	v_log_f32_e32 v51, v3
	v_max_f32_e32 v3, v4, v4
	v_max_f32_e32 v52, 0, v3
	v_add_f32_e32 v3, 1.0, v5
	v_mul_f32_e64 v5, |v44|, s79
	v_exp_f32_e32 v5, v5
	v_log_f32_e32 v54, v3
	v_max_f32_e32 v3, v44, v44
	v_max_f32_e32 v53, 0, v3
	v_add_f32_e32 v3, 1.0, v5
	v_mul_f32_e64 v5, |v6|, s79
	v_exp_f32_e32 v5, v5
	v_log_f32_e32 v55, v3
	v_max_f32_e32 v3, v6, v6
	v_max_f32_e32 v56, 0, v3
	v_add_f32_e32 v3, 1.0, v5
	v_mul_f32_e64 v5, |v10|, s79
	v_exp_f32_e32 v5, v5
	v_log_f32_e32 v58, v3
	v_max_f32_e32 v3, v10, v10
	v_max_f32_e32 v57, 0, v3
	v_add_f32_e32 v3, 1.0, v5
	v_mul_f32_e64 v5, |v8|, s79
	v_exp_f32_e32 v5, v5
	v_log_f32_e32 v59, v3
	v_max_f32_e32 v3, v8, v8
	v_max_f32_e32 v60, 0, v3
	v_add_f32_e32 v3, 1.0, v5
	v_mul_f32_e64 v5, |v9|, s79
	v_exp_f32_e32 v5, v5
	v_log_f32_e32 v62, v3
	v_max_f32_e32 v3, v9, v9
	v_max_f32_e32 v61, 0, v3
	v_add_f32_e32 v3, 1.0, v5
	v_mul_f32_e64 v5, |v2|, s79
	v_exp_f32_e32 v5, v5
	v_log_f32_e32 v63, v3
	v_max_f32_e32 v3, v2, v2
	v_max_f32_e32 v64, 0, v3
	v_add_f32_e32 v3, 1.0, v5
	v_mul_f32_e64 v5, |v12|, s79
	v_exp_f32_e32 v5, v5
	v_log_f32_e32 v78, v3
	v_max_f32_e32 v3, v12, v12
	v_max_f32_e32 v65, 0, v3
	v_add_f32_e32 v3, 1.0, v5
	v_mul_f32_e64 v5, |v14|, s79
	v_exp_f32_e32 v5, v5
	v_log_f32_e32 v79, v3
	v_max_f32_e32 v3, v14, v14
	v_max_f32_e32 v80, 0, v3
	v_add_f32_e32 v3, 1.0, v5
	v_mul_f32_e64 v5, |v16|, s79
	v_exp_f32_e32 v5, v5
	v_log_f32_e32 v114, v3
	v_max_f32_e32 v3, v16, v16
	v_max_f32_e32 v81, 0, v3
	v_add_f32_e32 v3, 1.0, v5
	v_mul_f32_e64 v5, |v38|, s79
	v_exp_f32_e32 v5, v5
	v_log_f32_e32 v115, v3
	v_max_f32_e32 v3, v38, v38
	v_max_f32_e32 v116, 0, v3
	v_add_f32_e32 v3, 1.0, v5
	v_mul_f32_e64 v5, |v15|, s79
	v_exp_f32_e32 v5, v5
	v_log_f32_e32 v118, v3
	v_max_f32_e32 v3, v15, v15
	v_max_f32_e32 v117, 0, v3
	v_add_f32_e32 v3, 1.0, v5
	v_cndmask_b32_e64 v17, v211, v17, s[68:69]
	v_log_f32_e32 v119, v3
	v_mul_f32_e64 v3, |v41|, s79
	v_exp_f32_e32 v3, v3
	v_mul_f32_e64 v5, |v17|, s79
	v_exp_f32_e32 v5, v5
	v_pk_fma_f32 v[64:65], v[78:79], s[74:75], v[64:65] op_sel_hi:[1,0,1]
	v_add_f32_e32 v3, 1.0, v3
	v_log_f32_e32 v121, v3
	v_add_f32_e32 v3, 1.0, v5
	v_log_f32_e32 v120, v3
	v_pk_fma_f32 v[80:81], v[114:115], s[74:75], v[80:81] op_sel_hi:[1,0,1]
	v_sub_f32_e64 v5, -v64, v65
	v_sub_f32_e32 v5, v5, v80
	v_max_f32_e32 v7, v41, v41
	v_max_f32_e32 v3, v17, v17
	v_pk_fma_f32 v[116:117], v[118:119], s[74:75], v[116:117] op_sel_hi:[1,0,1]
	v_sub_f32_e32 v5, v5, v81
	v_max_f32_e32 v123, 0, v7
	v_max_f32_e32 v122, 0, v3
	v_sub_f32_e32 v5, v5, v116
	v_pk_fma_f32 v[120:121], v[120:121], s[74:75], v[122:123] op_sel_hi:[1,0,1]
	v_sub_f32_e32 v5, v5, v117
	v_sub_f32_e32 v5, v5, v121
	v_sub_f32_e32 v123, v5, v120
	v_mov_b32_e32 v5, v123
	v_mov_b32_e32 v7, v123
	s_nop 1
	v_permlane32_swap_b32_e32 v5, v7
	v_pk_fma_f32 v[48:49], v[50:51], s[74:75], v[48:49] op_sel_hi:[1,0,1]
	v_cndmask_b32_e64 v122, v5, v7, s[38:39]
	v_pk_fma_f32 v[52:53], v[54:55], s[74:75], v[52:53] op_sel_hi:[1,0,1]
	v_sub_f32_e64 v7, -v48, v49
	v_sub_f32_e32 v7, v7, v52
	v_pk_fma_f32 v[56:57], v[58:59], s[74:75], v[56:57] op_sel_hi:[1,0,1]
	v_sub_f32_e32 v7, v7, v53
	v_sub_f32_e32 v7, v7, v56
	v_pk_fma_f32 v[60:61], v[62:63], s[74:75], v[60:61] op_sel_hi:[1,0,1]
	v_sub_f32_e32 v7, v7, v57
	v_sub_f32_e32 v7, v7, v60
	v_sub_f32_e32 v125, v7, v61
	v_sub_f32_e32 v5, v9, v61
	v_mov_b32_e32 v7, v125
	v_mov_b32_e32 v9, v125
	s_nop 1
	v_permlane32_swap_b32_e32 v7, v9
	v_cndmask_b32_e64 v124, v7, v9, s[38:39]
	v_add_f32_e32 v7, v123, v124
	v_cmp_gt_u32_e64 s[42:43], 32, v39
	v_pk_mov_b32 v[58:59], v[56:57], v[60:61] op_sel:[1,0]
	v_pk_mov_b32 v[54:55], v[52:53], v[56:57] op_sel:[1,0]
	v_cndmask_b32_e64 v7, v123, v7, s[42:43]
	v_add_f32_e32 v7, v7, v122
	v_add_f32_e32 v9, 0, v7
	v_add_f32_e32 v5, v5, v9
	v_mul_f32_e32 v5, 0x3fb8aa3b, v5
	v_pk_add_f32 v[8:9], v[8:9], v[60:61] neg_lo:[0,1] neg_hi:[0,1]
	v_exp_f32_e32 v50, v5
	v_add_f32_e32 v5, v8, v9
	v_mov_b32_e32 v11, v9
	v_mul_f32_e32 v5, 0x3fb8aa3b, v5
	v_pk_add_f32 v[8:9], v[10:11], v[58:59] neg_lo:[0,1] neg_hi:[0,1]
	v_exp_f32_e32 v51, v5
	v_add_f32_e32 v5, v8, v9
	v_mov_b32_e32 v7, v9
	v_mul_f32_e32 v5, 0x3fb8aa3b, v5
	v_pk_add_f32 v[6:7], v[6:7], v[56:57] neg_lo:[0,1] neg_hi:[0,1]
	v_exp_f32_e32 v8, v5
	v_add_f32_e32 v5, v6, v7
	v_mov_b32_e32 v45, v7
	v_mul_f32_e32 v5, 0x3fb8aa3b, v5
	v_pk_add_f32 v[6:7], v[44:45], v[54:55] neg_lo:[0,1] neg_hi:[0,1]
	v_exp_f32_e32 v9, v5
	v_add_f32_e32 v5, v6, v7
	v_mul_f32_e32 v5, 0x3fb8aa3b, v5
	v_exp_f32_e32 v6, v5
	v_mov_b32_e32 v5, v7
	v_pk_add_f32 v[4:5], v[4:5], v[52:53] neg_lo:[0,1] neg_hi:[0,1]
	v_sub_f32_e32 v3, v17, v120
	v_add_f32_e32 v4, v4, v5
	v_mul_f32_e32 v4, 0x3fb8aa3b, v4
	v_exp_f32_e32 v7, v4
	v_mov_b32_e32 v47, v5
	v_pk_mov_b32 v[4:5], v[48:49], v[52:53] op_sel:[1,0]
	v_mov_b32_e32 v118, v117
	v_pk_add_f32 v[4:5], v[46:47], v[4:5] neg_lo:[0,1] neg_hi:[0,1]
	v_mov_b32_e32 v119, v121
	v_add_f32_e32 v4, v4, v5
	v_mul_f32_e32 v4, 0x3fb8aa3b, v4
	v_mov_b32_e32 v43, v5
	v_exp_f32_e32 v10, v4
	v_pk_add_f32 v[4:5], v[42:43], v[48:49] neg_lo:[0,1] neg_hi:[0,1]
	v_pk_mov_b32 v[114:115], v[80:81], v[116:117] op_sel:[1,0]
	v_add_f32_e32 v4, v4, v5
	v_mul_f32_e32 v4, 0x3fb8aa3b, v4
	v_exp_f32_e32 v11, v4
	v_add_f32_e32 v4, 0, v122
	v_cndmask_b32_e64 v40, 0, v4, s[42:43]
	v_add_f32_e32 v3, v40, v3
	v_mul_f32_e32 v3, 0x3fb8aa3b, v3
	v_pk_add_f32 v[4:5], v[40:41], v[120:121] neg_lo:[0,1] neg_hi:[0,1]
	v_exp_f32_e32 v42, v3
	v_add_f32_e32 v3, v4, v5
	v_pk_mov_b32 v[4:5], v[14:15], v[4:5] op_sel:[1,0]
	v_mul_f32_e32 v40, 0x3fb8aa3b, v3
	v_pk_add_f32 v[4:5], v[4:5], v[118:119] neg_lo:[0,1] neg_hi:[0,1]
	s_nop 0
	v_mov_b32_e32 v39, v5
	v_add_f32_e32 v3, v4, v5
	v_pk_add_f32 v[4:5], v[38:39], v[116:117] neg_lo:[0,1] neg_hi:[0,1]
	v_mul_f32_e32 v3, 0x3fb8aa3b, v3
	v_mov_b32_e32 v17, v5
	v_exp_f32_e32 v41, v3
	v_add_f32_e32 v3, v4, v5
	v_pk_add_f32 v[4:5], v[16:17], v[114:115] neg_lo:[0,1] neg_hi:[0,1]
	v_mul_f32_e32 v38, 0x3fb8aa3b, v3
	v_add_f32_e32 v3, v4, v5
	v_mov_b32_e32 v15, v5
	v_mul_f32_e32 v3, 0x3fb8aa3b, v3
	v_pk_add_f32 v[4:5], v[14:15], v[80:81] neg_lo:[0,1] neg_hi:[0,1]
	v_exp_f32_e32 v16, v3
	v_add_f32_e32 v3, v4, v5
	v_mov_b32_e32 v13, v5
	v_pk_mov_b32 v[4:5], v[64:65], v[80:81] op_sel:[1,0]
	v_mul_f32_e32 v14, 0x3fb8aa3b, v3
	v_pk_add_f32 v[4:5], v[12:13], v[4:5] neg_lo:[0,1] neg_hi:[0,1]
	s_nop 0
	v_add_f32_e32 v3, v4, v5
	v_mul_f32_e32 v3, 0x3fb8aa3b, v3
	v_exp_f32_e32 v12, v3
	v_mov_b32_e32 v3, v5
	v_pk_add_f32 v[2:3], v[2:3], v[64:65] neg_lo:[0,1] neg_hi:[0,1]
	s_nop 0
	v_add_f32_e32 v2, v2, v3
	v_mul_f32_e32 v2, 0x3fb8aa3b, v2
	v_exp_f32_e32 v13, v2
	v_cvt_pk_bf16_f32 v2, v11, v10
	v_cvt_pk_bf16_f32 v3, v7, v6
	v_cvt_pk_bf16_f32 v4, v9, v8
	v_cvt_pk_bf16_f32 v5, v51, v50
	v_exp_f32_e32 v6, v14
	s_waitcnt lgkmcnt(7)
	v_mfma_f32_32x32x16_bf16 v[50:65], v[34:37], v[2:5], 0
	v_exp_f32_e32 v7, v38
	v_exp_f32_e32 v8, v40
	v_cvt_pk_bf16_f32 v78, v13, v12
	v_cvt_pk_bf16_f32 v79, v6, v16
	v_cvt_pk_bf16_f32 v80, v7, v41
	v_cvt_pk_bf16_f32 v81, v8, v42
	s_waitcnt lgkmcnt(6)
	v_mfma_f32_32x32x16_bf16 v[34:49], v[18:21], v[2:5], 0
	s_waitcnt lgkmcnt(5)
	v_mfma_f32_32x32x16_bf16 v[50:65], v[30:33], v[78:81], v[50:65]
	s_waitcnt lgkmcnt(4)
	v_mfma_f32_32x32x16_bf16 v[34:49], v[22:25], v[78:81], v[34:49]
	s_waitcnt lgkmcnt(3)
	v_mfma_f32_32x32x16_bf16 v[18:33], v[26:29], v[2:5], 0
	s_waitcnt lgkmcnt(2)
	v_mfma_f32_32x32x16_bf16 v[2:17], v[70:73], v[2:5], 0
	v_add_f32_e64 v70, v124, v122
	v_add_f32_e64 v71, v125, v123
	v_add_f32_e32 v70, v70, v71
	v_cmp_gt_f32_e32 vcc, s88, v70
	s_cmp_eq_u64 vcc, exec
	s_cselect_b64 s[0:1], -1, 0
	s_cmp_eq_u32 s27, 0
	s_waitcnt lgkmcnt(1)
	v_mfma_f32_32x32x16_bf16 v[18:33], v[74:77], v[78:81], v[18:33]
	s_cselect_b64 s[8:9], -1, 0
	s_or_b64 s[0:1], s[8:9], s[0:1]
	s_and_b64 vcc, exec, s[0:1]
	s_waitcnt lgkmcnt(0)
	v_mfma_f32_32x32x16_bf16 v[2:17], v[66:69], v[78:81], v[2:17]
	s_cbranch_vccnz .LBB0_246
	s_and_b32 s0, s14, 0xff
	s_lshl_b32 s0, s0, 5
	s_sub_i32 s84, s0, 32
	v_add_f32_e32 v190, 0, v70
	v_readfirstlane_b32 s18, v150
	v_readfirstlane_b32 s19, v151
	v_readfirstlane_b32 s30, v152
	v_readfirstlane_b32 s31, v153
	v_and_b32_e32 v216, 63, v208
	v_lshrrev_b32_e32 v213, 4, v216
	v_and_b32_e32 v214, 15, v216
	v_xor_b32_e32 v214, v214, v213
	v_lshlrev_b32_e32 v214, 4, v214
	v_lshl_or_b32 v212, v213, 12, v214
	v_and_b32_e32 v218, 3, v216
	v_xor_b32_e32 v218, v218, v213
	v_lshlrev_b32_e32 v218, 4, v218
	v_lshrrev_b32_e32 v217, 2, v216
	v_lshl_or_b32 v216, v217, 6, v218
	v_xor_b32_e32 v213, 64, v212
	v_xor_b32_e32 v214, 0x80, v212
	v_xor_b32_e32 v215, 0xc0, v212
.LBB0_249:
	s_add_i32 s8, s27, -1
	s_lshl_b64 s[0:1], s[84:85], 12
	s_add_u32 s100, s18, s0
	s_addc_u32 s101, s19, s1
	s_mov_b32 m0, s33
	s_nop 0
	global_load_lds_dwordx4 v212, s[100:101]
	s_add_u32 s100, s100, 0x3c00
	s_addc_u32 s101, s101, 0
	global_load_lds_dwordx4 v213, s[100:101] offset:1024
	s_add_u32 s100, s100, 0x3c00
	s_addc_u32 s101, s101, 0
	global_load_lds_dwordx4 v214, s[100:101] offset:2048
	s_add_u32 s100, s100, 0x3c00
	s_addc_u32 s101, s101, 0
	global_load_lds_dwordx4 v215, s[100:101] offset:3072
	s_add_u32 s100, s100, 0x4c00
	s_addc_u32 s101, s101, 0
	s_add_i32 m0, s33, 0x1000
	s_nop 0
	global_load_lds_dwordx4 v212, s[100:101]
	s_add_u32 s100, s100, 0x3c00
	s_addc_u32 s101, s101, 0
	global_load_lds_dwordx4 v213, s[100:101] offset:1024
	s_add_u32 s100, s100, 0x3c00
	s_addc_u32 s101, s101, 0
	global_load_lds_dwordx4 v214, s[100:101] offset:2048
	s_add_u32 s100, s100, 0x3c00
	s_addc_u32 s101, s101, 0
	global_load_lds_dwordx4 v215, s[100:101] offset:3072
	s_lshr_b32 s0, s8, 1
	s_mov_b32 s1, s85
	s_lshl_b64 s[0:1], s[0:1], 18
	s_add_u32 s100, s30, s0
	s_addc_u32 s101, s31, s1
	s_and_b32 s6, s84, 32
	s_lshl_b32 s0, s6, 12
	s_add_u32 s100, s100, s0
	s_addc_u32 s101, s101, 0
	s_add_i32 m0, s33, 0x2000
	s_nop 0
	global_load_lds_dwordx4 v216, s[100:101]
	global_load_lds_dwordx4 v216, s[100:101] offset:1024
	global_load_lds_dwordx4 v216, s[100:101] offset:2048
	global_load_lds_dwordx4 v216, s[100:101] offset:3072
	s_add_u32 s100, s100, 0x1000
	s_addc_u32 s101, s101, 0
	s_add_i32 m0, s33, 0x3000
	s_nop 0
	global_load_lds_dwordx4 v216, s[100:101]
	global_load_lds_dwordx4 v216, s[100:101] offset:1024
	global_load_lds_dwordx4 v216, s[100:101] offset:2048
	global_load_lds_dwordx4 v216, s[100:101] offset:3072
	s_waitcnt vmcnt(0)
	ds_read_b128 v[66:69], v179
	ds_read_b128 v[114:117], v180
	ds_read_b128 v[118:121], v181
	ds_read_b128 v[122:125], v182
	ds_read_b128 v[126:129], v184
	ds_read_b128 v[130:133], v185
	ds_read_b128 v[134:137], v186
	ds_read_b128 v[138:141], v187
	s_waitcnt lgkmcnt(7)
	v_mfma_f32_32x32x16_bf16 v[66:81], v[66:69], v[82:85], 0
	s_waitcnt lgkmcnt(6)
	v_mfma_f32_32x32x16_bf16 v[66:81], v[114:117], v[86:89], v[66:81]
	s_waitcnt lgkmcnt(5)
	v_mfma_f32_32x32x16_bf16 v[66:81], v[118:121], v[90:93], v[66:81]
	s_waitcnt lgkmcnt(4)
	v_mfma_f32_32x32x16_bf16 v[66:81], v[122:125], v[94:97], v[66:81]
	s_waitcnt lgkmcnt(3)
	v_mfma_f32_32x32x16_bf16 v[66:81], v[126:129], v[98:101], v[66:81]
	s_waitcnt lgkmcnt(2)
	v_mfma_f32_32x32x16_bf16 v[66:81], v[130:133], v[102:105], v[66:81]
	s_waitcnt lgkmcnt(1)
	v_mfma_f32_32x32x16_bf16 v[66:81], v[134:137], v[106:109], v[66:81]
	s_waitcnt lgkmcnt(0)
	v_mfma_f32_32x32x16_bf16 v[66:81], v[138:141], v[110:113], v[66:81]
	ds_read_b128 v[114:117], v189 offset:14336
	ds_read_b128 v[118:121], v188 offset:14336
	ds_read_b128 v[122:125], v189 offset:12288
	ds_read_b128 v[126:129], v188 offset:12288
	ds_read_b128 v[130:133], v189 offset:10240
	ds_read_b128 v[134:137], v188 offset:10240
	ds_read_b128 v[138:141], v189 offset:8192
	ds_read_b128 v[142:145], v188 offset:8192
	s_nop 3
	v_mul_f32_e64 v155, |v66|, s79
	v_mul_f32_e64 v157, |v67|, s79
	v_exp_f32_e32 v155, v155
	v_exp_f32_e32 v157, v157
	v_max_f32_e32 v154, v66, v66
	v_max_f32_e32 v154, 0, v154
	v_add_f32_e32 v155, 1.0, v155
	v_add_f32_e32 v157, 1.0, v157
	v_log_f32_e32 v156, v155
	v_log_f32_e32 v157, v157
	v_max_f32_e32 v155, v67, v67
	v_max_f32_e32 v155, 0, v155
	v_mul_f32_e64 v159, |v69|, s79
	v_pk_fma_f32 v[156:157], v[156:157], s[74:75], v[154:155] op_sel_hi:[1,0,1]
	v_mul_f32_e64 v155, |v68|, s79
	v_exp_f32_e32 v155, v155
	v_exp_f32_e32 v159, v159
	v_max_f32_e32 v154, v68, v68
	v_max_f32_e32 v154, 0, v154
	v_add_f32_e32 v155, 1.0, v155
	v_add_f32_e32 v159, 1.0, v159
	v_log_f32_e32 v158, v155
	v_log_f32_e32 v159, v159
	v_max_f32_e32 v155, v69, v69
	v_max_f32_e32 v155, 0, v155
	v_sub_f32_e64 v162, -v156, v157
	v_pk_fma_f32 v[160:161], v[158:159], s[74:75], v[154:155] op_sel_hi:[1,0,1]
	v_mul_f32_e64 v155, |v70|, s79
	v_mul_f32_e64 v159, |v71|, s79
	v_exp_f32_e32 v155, v155
	v_exp_f32_e32 v159, v159
	v_sub_f32_e32 v154, v162, v160
	v_sub_f32_e32 v162, v154, v161
	v_add_f32_e32 v155, 1.0, v155
	v_add_f32_e32 v159, 1.0, v159
	v_log_f32_e32 v158, v155
	v_log_f32_e32 v159, v159
	v_max_f32_e32 v154, v70, v70
	v_max_f32_e32 v155, v71, v71
	v_max_f32_e32 v154, 0, v154
	v_max_f32_e32 v155, 0, v155
	v_pk_fma_f32 v[164:165], v[158:159], s[74:75], v[154:155] op_sel_hi:[1,0,1]
	v_mul_f32_e64 v155, |v72|, s79
	v_mul_f32_e64 v159, |v73|, s79
	v_exp_f32_e32 v155, v155
	v_exp_f32_e32 v159, v159
	v_sub_f32_e32 v154, v162, v164
	v_sub_f32_e32 v162, v154, v165
	v_add_f32_e32 v155, 1.0, v155
	v_add_f32_e32 v159, 1.0, v159
	v_log_f32_e32 v158, v155
	v_log_f32_e32 v159, v159
	v_max_f32_e32 v154, v72, v72
	v_max_f32_e32 v155, v73, v73
	v_max_f32_e32 v154, 0, v154
	v_max_f32_e32 v155, 0, v155
	v_pk_fma_f32 v[168:169], v[158:159], s[74:75], v[154:155] op_sel_hi:[1,0,1]
	s_nop 0
	v_sub_f32_e32 v191, v73, v169
	v_max_f32_e32 v73, v74, v74
	v_max_f32_e32 v158, 0, v73
	v_mul_f32_e64 v73, |v74|, s79
	v_exp_f32_e32 v73, v73
	v_sub_f32_e32 v154, v162, v168
	v_sub_f32_e32 v155, v154, v169
	v_max_f32_e32 v154, v76, v76
	v_add_f32_e32 v73, 1.0, v73
	v_log_f32_e32 v162, v73
	v_max_f32_e32 v73, v75, v75
	v_max_f32_e32 v159, 0, v73
	v_mul_f32_e64 v73, |v75|, s79
	v_exp_f32_e32 v73, v73
	s_nop 0
	v_add_f32_e32 v73, 1.0, v73
	v_log_f32_e32 v163, v73
	s_nop 0
	v_pk_fma_f32 v[158:159], v[162:163], s[74:75], v[158:159] op_sel_hi:[1,0,1]
	v_max_f32_e32 v162, 0, v154
	v_mul_f32_e64 v154, |v76|, s79
	v_exp_f32_e32 v154, v154
	v_sub_f32_e64 v73, -v158, v159
	v_add_f32_e32 v154, 1.0, v154
	v_log_f32_e32 v166, v154
	v_max_f32_e32 v154, v77, v77
	v_max_f32_e32 v163, 0, v154
	v_mul_f32_e64 v154, |v77|, s79
	v_exp_f32_e32 v154, v154
	s_nop 0
	v_add_f32_e32 v154, 1.0, v154
	v_log_f32_e32 v167, v154
	v_max_f32_e32 v154, v78, v78
	v_pk_fma_f32 v[162:163], v[166:167], s[74:75], v[162:163] op_sel_hi:[1,0,1]
	v_max_f32_e32 v166, 0, v154
	v_mul_f32_e64 v154, |v78|, s79
	v_exp_f32_e32 v154, v154
	v_sub_f32_e32 v73, v73, v162
	v_sub_f32_e32 v73, v73, v163
	v_add_f32_e32 v154, 1.0, v154
	v_log_f32_e32 v170, v154
	v_max_f32_e32 v154, v79, v79
	v_max_f32_e32 v167, 0, v154
	v_mul_f32_e64 v154, |v79|, s79
	v_exp_f32_e32 v154, v154
	s_nop 0
	v_add_f32_e32 v154, 1.0, v154
	v_log_f32_e32 v171, v154
	v_max_f32_e32 v154, v80, v80
	v_pk_fma_f32 v[166:167], v[170:171], s[74:75], v[166:167] op_sel_hi:[1,0,1]
	v_max_f32_e32 v170, 0, v154
	v_mul_f32_e64 v154, |v80|, s79
	v_exp_f32_e32 v154, v154
	v_sub_f32_e32 v73, v73, v166
	v_sub_f32_e32 v73, v73, v167
	v_add_f32_e32 v154, 1.0, v154
	v_log_f32_e32 v172, v154
	v_max_f32_e32 v154, v81, v81
	v_max_f32_e32 v171, 0, v154
	v_mul_f32_e64 v154, |v81|, s79
	v_exp_f32_e32 v154, v154
	s_nop 0
	v_add_f32_e32 v154, 1.0, v154
	v_log_f32_e32 v173, v154
	s_nop 0
	v_pk_fma_f32 v[172:173], v[172:173], s[74:75], v[170:171] op_sel_hi:[1,0,1]
	s_nop 0
	v_sub_f32_e32 v73, v73, v172
	v_sub_f32_e32 v196, v81, v173
	v_sub_f32_e32 v171, v73, v173
	v_mov_b32_e32 v73, v155
	v_mov_b32_e32 v81, v155
	s_nop 1
	v_permlane32_swap_b32_e32 v73, v81
	v_cndmask_b32_e64 v154, v73, v81, s[38:39]
	v_mov_b32_e32 v73, v171
	v_mov_b32_e32 v81, v171
	s_nop 1
	v_permlane32_swap_b32_e32 v73, v81
	v_cndmask_b32_e64 v170, v73, v81, s[38:39]
	v_add_f32_e32 v73, v171, v154
	v_cndmask_b32_e64 v73, v171, v73, s[42:43]
	v_add_f32_e32 v73, v73, v170
	v_add_f32_e32 v73, v190, v73
	v_pk_add_f32 v[192:193], v[72:73], v[168:169] neg_lo:[0,1] neg_hi:[0,1]
	v_pk_mov_b32 v[168:169], v[164:165], v[168:169] op_sel:[1,0]
	v_add_f32_e32 v72, v192, v193
	v_mov_b32_e32 v192, v71
	v_pk_add_f32 v[168:169], v[192:193], v[168:169] neg_lo:[0,1] neg_hi:[0,1]
	v_add_f32_e32 v81, v191, v73
	v_add_f32_e32 v71, v168, v169
	v_mul_f32_e32 v71, 0x3fb8aa3b, v71
	v_exp_f32_e32 v73, v71
	v_mov_b32_e32 v71, v169
	v_pk_add_f32 v[168:169], v[70:71], v[164:165] neg_lo:[0,1] neg_hi:[0,1]
	v_pk_mov_b32 v[164:165], v[160:161], v[164:165] op_sel:[1,0]
	v_add_f32_e32 v70, v168, v169
	v_mov_b32_e32 v168, v69
	v_pk_add_f32 v[164:165], v[168:169], v[164:165] neg_lo:[0,1] neg_hi:[0,1]
	v_mul_f32_e32 v81, 0x3fb8aa3b, v81
	v_add_f32_e32 v69, v164, v165
	v_mul_f32_e32 v69, 0x3fb8aa3b, v69
	v_exp_f32_e32 v71, v69
	v_mov_b32_e32 v69, v165
	v_pk_add_f32 v[164:165], v[68:69], v[160:161] neg_lo:[0,1] neg_hi:[0,1]
	v_pk_mov_b32 v[160:161], v[156:157], v[160:161] op_sel:[1,0]
	v_add_f32_e32 v68, v164, v165
	v_mov_b32_e32 v164, v67
	v_pk_add_f32 v[160:161], v[164:165], v[160:161] neg_lo:[0,1] neg_hi:[0,1]
	v_exp_f32_e32 v191, v81
	v_add_f32_e32 v67, v160, v161
	v_mul_f32_e32 v67, 0x3fb8aa3b, v67
	v_exp_f32_e32 v69, v67
	v_mov_b32_e32 v67, v161
	v_pk_add_f32 v[66:67], v[66:67], v[156:157] neg_lo:[0,1] neg_hi:[0,1]
	v_pk_mov_b32 v[160:161], v[166:167], v[172:173] op_sel:[1,0]
	v_add_f32_e32 v66, v66, v67
	v_mul_f32_e32 v66, 0x3fb8aa3b, v66
	v_exp_f32_e32 v67, v66
	v_cndmask_b32_e64 v66, 0, v170, s[42:43]
	v_add_f32_e32 v81, v190, v66
	v_pk_add_f32 v[156:157], v[80:81], v[172:173] neg_lo:[0,1] neg_hi:[0,1]
	v_add_f32_e32 v66, v196, v81
	v_add_f32_e32 v80, v156, v157
	v_mov_b32_e32 v156, v79
	v_pk_add_f32 v[156:157], v[156:157], v[160:161] neg_lo:[0,1] neg_hi:[0,1]
	v_mul_f32_e32 v72, 0x3fb8aa3b, v72
	v_add_f32_e32 v79, v156, v157
	v_mul_f32_e32 v79, 0x3fb8aa3b, v79
	v_exp_f32_e32 v81, v79
	v_mov_b32_e32 v79, v157
	v_pk_add_f32 v[78:79], v[78:79], v[166:167] neg_lo:[0,1] neg_hi:[0,1]
	v_pk_mov_b32 v[156:157], v[162:163], v[166:167] op_sel:[1,0]
	v_add_f32_e32 v78, v78, v79
	v_mul_f32_e32 v78, 0x3fb8aa3b, v78
	v_exp_f32_e32 v160, v78
	v_mov_b32_e32 v78, v77
	v_pk_add_f32 v[78:79], v[78:79], v[156:157] neg_lo:[0,1] neg_hi:[0,1]
	v_mul_f32_e32 v70, 0x3fb8aa3b, v70
	v_add_f32_e32 v77, v78, v79
	v_mul_f32_e32 v77, 0x3fb8aa3b, v77
	v_exp_f32_e32 v156, v77
	v_mov_b32_e32 v77, v79
	v_pk_add_f32 v[76:77], v[76:77], v[162:163] neg_lo:[0,1] neg_hi:[0,1]
	v_pk_mov_b32 v[78:79], v[158:159], v[162:163] op_sel:[1,0]
	v_add_f32_e32 v76, v76, v77
	v_mul_f32_e32 v76, 0x3fb8aa3b, v76
	v_exp_f32_e32 v157, v76
	v_mov_b32_e32 v76, v75
	v_pk_add_f32 v[76:77], v[76:77], v[78:79] neg_lo:[0,1] neg_hi:[0,1]
	v_mul_f32_e32 v68, 0x3fb8aa3b, v68
	v_add_f32_e32 v75, v76, v77
	v_mul_f32_e32 v75, 0x3fb8aa3b, v75
	v_exp_f32_e32 v72, v72
	v_exp_f32_e32 v70, v70
	v_exp_f32_e32 v68, v68
	v_exp_f32_e32 v161, v75
	v_mov_b32_e32 v75, v77
	v_cvt_pk_bf16_f32 v76, v67, v69
	v_cvt_pk_bf16_f32 v77, v68, v71
	v_cvt_pk_bf16_f32 v78, v70, v73
	v_cvt_pk_bf16_f32 v79, v72, v191
	v_pk_add_f32 v[74:75], v[74:75], v[158:159] neg_lo:[0,1] neg_hi:[0,1]
	s_waitcnt lgkmcnt(0)
	v_mfma_f32_32x32x16_bf16 v[50:65], v[142:145], v[76:79], v[50:65]
	v_add_f32_e32 v74, v74, v75
	v_mul_f32_e32 v74, 0x3fb8aa3b, v74
	v_mul_f32_e32 v66, 0x3fb8aa3b, v66
	v_mul_f32_e32 v80, 0x3fb8aa3b, v80
	v_exp_f32_e32 v158, v74
	v_pk_add_f32 v[74:75], v[154:155], v[170:171]
	v_exp_f32_e32 v66, v66
	v_mfma_f32_32x32x16_bf16 v[34:49], v[134:137], v[76:79], v[34:49]
	v_exp_f32_e32 v80, v80
	v_add_f32_e32 v74, v74, v75
	v_cvt_pk_bf16_f32 v68, v158, v161
	v_cvt_pk_bf16_f32 v69, v157, v156
	v_cvt_pk_bf16_f32 v70, v160, v81
	v_cvt_pk_bf16_f32 v71, v80, v66
	v_add_f32_e32 v190, v190, v74
	v_mfma_f32_32x32x16_bf16 v[18:33], v[126:129], v[76:79], v[18:33]
	v_cmp_gt_f32_e32 vcc, s88, v190
	s_cmp_lg_u64 vcc, exec
	s_cselect_b64 s[0:1], -1, 0
	s_cmp_gt_u32 s27, 1
	s_cselect_b64 s[10:11], -1, 0
	s_and_b64 s[0:1], s[0:1], s[10:11]
	s_sub_i32 s84, s84, 32
	v_mfma_f32_32x32x16_bf16 v[2:17], v[118:121], v[76:79], v[2:17]
	s_and_b64 vcc, exec, s[0:1]
	s_mov_b32 s27, s8
	v_mfma_f32_32x32x16_bf16 v[50:65], v[138:141], v[68:71], v[50:65]
	v_mfma_f32_32x32x16_bf16 v[34:49], v[130:133], v[68:71], v[34:49]
	v_mfma_f32_32x32x16_bf16 v[18:33], v[122:125], v[68:71], v[18:33]
	v_mfma_f32_32x32x16_bf16 v[2:17], v[114:117], v[68:71], v[2:17]
	s_cbranch_vccnz .LBB0_249
	s_branch .LBB0_246
